# early PLE-projection group = odd XCDs (blockIdx bit 0) instead of XCDs 4-7
# speedup vs baseline: 1.0144x; 1.0144x over previous
.LBB0_126:
	s_mov_b32 s99, 0
	s_cmp_lg_u32 s3, 0x100
	s_cbranch_scc1 .Lflag_done
	v_mbcnt_lo_u32_b32 v0, -1, 0
	v_mbcnt_hi_u32_b32 v0, -1, v0
	v_lshlrev_b32_e32 v1, 4, v0
	v_add_u32_e32 v1, 0xe000, v1
	global_load_dwordx4 v[4:7], v1, s[76:77]
	v_and_b32_e32 v2, 1, v0
	s_waitcnt vmcnt(0)
	v_readlane_b32 s4, v4, 0
	v_readlane_b32 s5, v5, 0
	v_readlane_b32 s6, v6, 0
	v_readlane_b32 s7, v7, 0
	v_readlane_b32 s8, v4, 1
	v_readlane_b32 s9, v5, 1
	v_readlane_b32 s10, v6, 1
	v_readlane_b32 s11, v7, 1
	v_cmp_eq_u32_e32 vcc, 1, v2
	v_mov_b32_e32 v8, s4
	v_mov_b32_e32 v9, s8
	v_cndmask_b32_e32 v8, v8, v9, vcc
	v_mov_b32_e32 v10, s5
	v_mov_b32_e32 v9, s9
	v_cndmask_b32_e32 v10, v10, v9, vcc
	v_mov_b32_e32 v11, s6
	v_mov_b32_e32 v9, s10
	v_cndmask_b32_e32 v11, v11, v9, vcc
	v_mov_b32_e32 v12, s7
	v_mov_b32_e32 v9, s11
	v_cndmask_b32_e32 v12, v12, v9, vcc
	v_xor_b32_e32 v8, v4, v8
	v_xor_b32_e32 v10, v5, v10
	v_xor_b32_e32 v11, v6, v11
	v_xor_b32_e32 v12, v7, v12
	v_or3_b32 v8, v8, v10, v11
	v_or_b32_e32 v8, v8, v12
	v_min_u32_e32 v9, v4, v5
	v_min3_u32 v9, v9, v6, v7
	v_cmp_ne_u32_e32 vcc, 0, v8
	v_cmp_eq_u32_e64 s[4:5], 0, v9
	s_nop 3
	s_or_b64 s[4:5], vcc, s[4:5]
	s_cmp_lg_u64 s[4:5], 0
	s_cbranch_scc1 .Lflag_done
	s_mov_b32 s99, 1
	s_bitcmp1_b32 s2, 0
	s_cbranch_scc0 .Lflag_done
	s_or_b32 s99, s99, 16
